# P2 K/V staging: all 8 loads in flight before the LDS writes; p3_reduce sample rows hand-written with all loads in flight
# speedup vs baseline: 1.0061x; 1.0061x over previous
.LBB0_709:
	s_ashr_i32 s20, s19, 2
	s_and_b32 s23, s19, 3
	s_lshl_b32 s24, s20, 7
	s_add_i32 s12, s24, 0xffffff80
	s_lshl_b32 s8, s23, 7
	s_mov_b32 s9, s92
	v_lshl_add_u64 v[14:15], v[132:133], 0, s[8:9]
	s_cmp_lt_i32 s12, 0
	v_lshl_add_u64 v[16:17], v[134:135], 0, s[8:9]
	s_barrier
	v_mov_b32_e32 v20, 0
	v_mov_b32_e32 v21, 0
	v_mov_b32_e32 v22, 0
	v_mov_b32_e32 v23, 0
	v_mov_b32_e32 v24, 0
	v_mov_b32_e32 v25, 0
	v_mov_b32_e32 v26, 0
	v_mov_b32_e32 v27, 0
	v_mov_b32_e32 v28, 0
	v_mov_b32_e32 v29, 0
	v_mov_b32_e32 v30, 0
	v_mov_b32_e32 v31, 0
	v_mov_b32_e32 v32, 0
	v_mov_b32_e32 v33, 0
	v_mov_b32_e32 v34, 0
	v_mov_b32_e32 v35, 0
	v_mov_b32_e32 v36, 0
	v_mov_b32_e32 v37, 0
	v_mov_b32_e32 v38, 0
	v_mov_b32_e32 v39, 0
	v_mov_b32_e32 v40, 0
	v_mov_b32_e32 v41, 0
	v_mov_b32_e32 v42, 0
	v_mov_b32_e32 v43, 0
	v_mov_b32_e32 v44, 0
	v_mov_b32_e32 v45, 0
	v_mov_b32_e32 v46, 0
	v_mov_b32_e32 v47, 0
	v_mov_b32_e32 v48, 0
	v_mov_b32_e32 v49, 0
	v_mov_b32_e32 v50, 0
	v_mov_b32_e32 v51, 0
	s_cbranch_scc1 .Lst_c1
	v_or_b32_e32 v130, s12, v177
	v_lshlrev_b64 v[52:53], 9, v[130:131]
	v_lshl_add_u64 v[54:55], v[14:15], 0, v[52:53]
	v_lshl_add_u64 v[56:57], v[16:17], 0, v[52:53]
	global_load_dwordx4 v[20:23], v[54:55], off
	global_load_dwordx4 v[24:27], v[56:57], off
.Lst_c1:
	v_add_u32_e32 v130, s12, v161
	v_cmp_lt_i32_e32 vcc, -1, v130
	s_and_saveexec_b64 s[8:9], vcc
	s_cbranch_execz .Lst_s0
	v_lshlrev_b64 v[52:53], 9, v[130:131]
	v_lshl_add_u64 v[54:55], v[14:15], 0, v[52:53]
	v_lshl_add_u64 v[56:57], v[16:17], 0, v[52:53]
	global_load_dwordx4 v[28:31], v[54:55], off
	global_load_dwordx4 v[32:35], v[56:57], off
.Lst_s0:
	s_or_b64 exec, exec, s[8:9]
	v_add_u32_e32 v130, s12, v162
	v_cmp_lt_i32_e32 vcc, -1, v130
	s_and_saveexec_b64 s[8:9], vcc
	s_cbranch_execz .Lst_s1
	v_lshlrev_b64 v[52:53], 9, v[130:131]
	v_lshl_add_u64 v[54:55], v[14:15], 0, v[52:53]
	v_lshl_add_u64 v[56:57], v[16:17], 0, v[52:53]
	global_load_dwordx4 v[36:39], v[54:55], off
	global_load_dwordx4 v[40:43], v[56:57], off
.Lst_s1:
	s_or_b64 exec, exec, s[8:9]
	v_add_u32_e32 v130, s12, v163
	v_cmp_lt_i32_e32 vcc, -1, v130
	s_and_saveexec_b64 s[8:9], vcc
	s_cbranch_execz .Lst_s2
	v_lshlrev_b64 v[52:53], 9, v[130:131]
	v_lshl_add_u64 v[54:55], v[14:15], 0, v[52:53]
	v_lshl_add_u64 v[56:57], v[16:17], 0, v[52:53]
	global_load_dwordx4 v[44:47], v[54:55], off
	global_load_dwordx4 v[48:51], v[56:57], off
.Lst_s2:
	s_or_b64 exec, exec, s[8:9]
	v_readlane_b32 s2, v254, 41
	v_readlane_b32 s3, v254, 42
	s_waitcnt vmcnt(6)
	ds_write_b128 v127, v[20:23]
	ds_write_b16 v175, v24 offset:36864
	ds_write_b16_d16_hi v175, v24 offset:37384
	ds_write_b16 v175, v25 offset:37904
	ds_write_b16_d16_hi v175, v25 offset:38424
	ds_write_b16 v175, v26 offset:38944
	ds_write_b16_d16_hi v175, v26 offset:39464
	ds_write_b16 v175, v27 offset:39984
	ds_write_b16_d16_hi v175, v27 offset:40504
	s_waitcnt vmcnt(4)
	ds_write_b128 v164, v[28:31]
	ds_write_b16 v165, v32 offset:36864
	ds_write_b16_d16_hi v165, v32 offset:37384
	ds_write_b16 v165, v33 offset:37904
	ds_write_b16_d16_hi v165, v33 offset:38424
	ds_write_b16 v165, v34 offset:38944
	ds_write_b16_d16_hi v165, v34 offset:39464
	ds_write_b16 v165, v35 offset:39984
	ds_write_b16_d16_hi v165, v35 offset:40504
	s_waitcnt vmcnt(2)
	ds_write_b128 v166, v[36:39]
	ds_write_b16 v175, v40 offset:37120
	ds_write_b16_d16_hi v175, v40 offset:37640
	ds_write_b16 v175, v41 offset:38160
	ds_write_b16_d16_hi v175, v41 offset:38680
	ds_write_b16 v175, v42 offset:39200
	ds_write_b16_d16_hi v175, v42 offset:39720
	ds_write_b16 v175, v43 offset:40240
	ds_write_b16_d16_hi v175, v43 offset:40760
	s_waitcnt vmcnt(0)
	ds_write_b128 v167, v[44:47]
	ds_write_b16 v173, v48 offset:36864
	ds_write_b16_d16_hi v173, v48 offset:37384
	ds_write_b16 v173, v49 offset:37904
	ds_write_b16_d16_hi v173, v49 offset:38424
	ds_write_b16 v173, v50 offset:38944
	ds_write_b16_d16_hi v173, v50 offset:39464
	ds_write_b16 v173, v51 offset:39984
	ds_write_b16_d16_hi v173, v51 offset:40504


	s_and_saveexec_b64 s[8:9], s[2:3]
	s_cbranch_execz .LBB0_720
	v_readlane_b32 s2, v255, 37
	s_nop 1
	v_mov_b32_e32 v0, s2
	ds_write_b32 v0, v131

.LBB0_1100:
	s_or_b64 exec, exec, s[2:3]
	v_readlane_b32 s12, v254, 2
	v_readlane_b32 s13, v254, 3
	s_mov_b64 s[4:5], s[12:13]
	s_add_u32 s2, s4, 0x13194400
	s_addc_u32 s3, s5, 0
	v_readlane_b32 s4, v254, 44
	s_cmpk_gt_i32 s4, 1
	s_waitcnt lgkmcnt(0)
	s_barrier
	v_readlane_b32 s14, v254, 4
	v_readlane_b32 s15, v254, 5
	v_readlane_b32 s5, v254, 48
	s_cbranch_scc1 .LBB0_1105
	v_readlane_b32 s4, v254, 0
	v_readlane_b32 s5, v254, 44
	v_readlane_b32 s14, v254, 8
	v_readlane_b32 s15, v254, 9
	v_readlane_b32 s16, v254, 2
	v_readlane_b32 s17, v254, 3
	v_readlane_b32 s18, v254, 36
	v_readlane_b32 s19, v254, 37
	v_readlane_b32 s22, v254, 30
	v_readlane_b32 s23, v254, 31
	s_lshl_b32 s4, s4, 1
	s_add_i32 s12, s4, s5
	s_lshl_b32 s13, s12, 13
	s_add_u32 s14, s14, s13
	s_addc_u32 s15, s15, 0
	s_add_u32 s28, s16, 0x131a4400
	s_addc_u32 s29, s17, 0
	s_add_u32 s28, s28, s13
	s_addc_u32 s29, s29, 0
	s_add_u32 s30, s22, 0x1000
	s_addc_u32 s31, s23, 0
	v_lshlrev_b32_e32 v0, 4, v170
	v_lshlrev_b32_e32 v1, 3, v170
	s_add_u32 s24, s14, 0x1000
	s_addc_u32 s25, s15, 0
	global_load_dwordx4 v[4:7], v0, s[14:15] nt
	global_load_dwordx4 v[8:11], v0, s[14:15] offset:1024 nt
	global_load_dwordx4 v[12:15], v0, s[14:15] offset:2048 nt
	global_load_dwordx4 v[16:19], v0, s[14:15] offset:3072 nt
	global_load_dwordx4 v[20:23], v0, s[24:25] nt
	global_load_dwordx4 v[24:27], v0, s[24:25] offset:1024 nt
	global_load_dwordx4 v[28:31], v0, s[24:25] offset:2048 nt
	global_load_dwordx4 v[32:35], v0, s[24:25] offset:3072 nt
	s_add_u32 s26, s28, 0x1000
	s_addc_u32 s27, s29, 0
	global_load_dwordx4 v[36:39], v0, s[28:29]
	global_load_dwordx4 v[40:43], v0, s[28:29] offset:1024
	global_load_dwordx4 v[44:47], v0, s[28:29] offset:2048
	global_load_dwordx4 v[48:51], v0, s[28:29] offset:3072
	global_load_dwordx4 v[52:55], v0, s[26:27]
	global_load_dwordx4 v[56:59], v0, s[26:27] offset:1024
	global_load_dwordx4 v[60:63], v0, s[26:27] offset:2048
	global_load_dwordx4 v[64:67], v0, s[26:27] offset:3072
	s_add_u32 s28, s28, 0x400000
	s_addc_u32 s29, s29, 0
	s_add_u32 s26, s28, 0x1000
	s_addc_u32 s27, s29, 0
	global_load_dwordx4 v[68:71], v0, s[28:29]
	global_load_dwordx4 v[72:75], v0, s[28:29] offset:1024
	global_load_dwordx4 v[76:79], v0, s[28:29] offset:2048
	global_load_dwordx4 v[80:83], v0, s[28:29] offset:3072
	global_load_dwordx4 v[84:87], v0, s[26:27]
	global_load_dwordx4 v[88:91], v0, s[26:27] offset:1024
	global_load_dwordx4 v[92:95], v0, s[26:27] offset:2048
	global_load_dwordx4 v[96:99], v0, s[26:27] offset:3072
	s_add_u32 s28, s28, 0x400000
	s_addc_u32 s29, s29, 0
	s_add_u32 s26, s28, 0x1000
	s_addc_u32 s27, s29, 0
	global_load_dwordx4 v[100:103], v0, s[28:29]
	global_load_dwordx4 v[104:107], v0, s[28:29] offset:1024
	global_load_dwordx4 v[108:111], v0, s[28:29] offset:2048
	global_load_dwordx4 v[112:115], v0, s[28:29] offset:3072
	global_load_dwordx4 v[116:119], v0, s[26:27]
	global_load_dwordx4 v[120:123], v0, s[26:27] offset:1024
	global_load_dwordx4 v[124:127], v0, s[26:27] offset:2048
	global_load_dwordx4 v[128:131], v0, s[26:27] offset:3072
	s_add_u32 s28, s28, 0x400000
	s_addc_u32 s29, s29, 0
	s_add_u32 s26, s28, 0x1000
	s_addc_u32 s27, s29, 0
	global_load_dwordx4 v[132:135], v0, s[28:29]
	global_load_dwordx4 v[136:139], v0, s[28:29] offset:1024
	global_load_dwordx4 v[140:143], v0, s[28:29] offset:2048
	global_load_dwordx4 v[144:147], v0, s[28:29] offset:3072
	global_load_dwordx4 v[148:151], v0, s[26:27]
	global_load_dwordx4 v[152:155], v0, s[26:27] offset:1024
	global_load_dwordx4 v[156:159], v0, s[26:27] offset:2048
	global_load_dwordx4 v[160:163], v0, s[26:27] offset:3072
	global_load_dwordx4 v[176:179], v0, s[22:23]
	global_load_dwordx4 v[180:183], v0, s[22:23] offset:1024
	global_load_dwordx4 v[184:187], v0, s[22:23] offset:2048
	global_load_dwordx4 v[188:191], v0, s[22:23] offset:3072
	global_load_dwordx4 v[192:195], v0, s[30:31]
	global_load_dwordx4 v[196:199], v0, s[30:31] offset:1024
	global_load_dwordx4 v[200:203], v0, s[30:31] offset:2048
	global_load_dwordx4 v[204:207], v0, s[30:31] offset:3072
	v_lshlrev_b32_e32 v2, 2, v170
	v_xor_b32_e32 v208, 4, v2
	v_xor_b32_e32 v209, 8, v2
	v_xor_b32_e32 v164, 16, v2
	v_xor_b32_e32 v165, 32, v2
	v_xor_b32_e32 v166, 64, v2
	v_xor_b32_e32 v167, 128, v2
	v_mov_b32_e32 v226, 0x358637bd
	s_waitcnt vmcnt(15)
	v_pk_add_f32 v[36:37], v[36:37], v[68:69]
	v_pk_add_f32 v[100:101], v[100:101], v[132:133]
	v_pk_add_f32 v[36:37], v[36:37], v[100:101]
	v_pk_add_f32 v[4:5], v[4:5], v[36:37]
	v_pk_mul_f32 v[222:223], v[4:5], v[4:5]
	v_pk_add_f32 v[38:39], v[38:39], v[70:71]
	v_pk_add_f32 v[102:103], v[102:103], v[134:135]
	v_pk_add_f32 v[38:39], v[38:39], v[102:103]
	v_pk_add_f32 v[6:7], v[6:7], v[38:39]
	v_pk_fma_f32 v[222:223], v[6:7], v[6:7], v[222:223]
	s_waitcnt vmcnt(14)
	v_pk_add_f32 v[40:41], v[40:41], v[72:73]
	v_pk_add_f32 v[104:105], v[104:105], v[136:137]
	v_pk_add_f32 v[40:41], v[40:41], v[104:105]
	v_pk_add_f32 v[8:9], v[8:9], v[40:41]
	v_pk_fma_f32 v[222:223], v[8:9], v[8:9], v[222:223]
	v_pk_add_f32 v[42:43], v[42:43], v[74:75]
	v_pk_add_f32 v[106:107], v[106:107], v[138:139]
	v_pk_add_f32 v[42:43], v[42:43], v[106:107]
	v_pk_add_f32 v[10:11], v[10:11], v[42:43]
	v_pk_fma_f32 v[222:223], v[10:11], v[10:11], v[222:223]
	s_waitcnt vmcnt(13)
	v_pk_add_f32 v[44:45], v[44:45], v[76:77]
	v_pk_add_f32 v[108:109], v[108:109], v[140:141]
	v_pk_add_f32 v[44:45], v[44:45], v[108:109]
	v_pk_add_f32 v[12:13], v[12:13], v[44:45]
	v_pk_fma_f32 v[222:223], v[12:13], v[12:13], v[222:223]
	v_pk_add_f32 v[46:47], v[46:47], v[78:79]
	v_pk_add_f32 v[110:111], v[110:111], v[142:143]
	v_pk_add_f32 v[46:47], v[46:47], v[110:111]
	v_pk_add_f32 v[14:15], v[14:15], v[46:47]
	v_pk_fma_f32 v[222:223], v[14:15], v[14:15], v[222:223]
	s_waitcnt vmcnt(12)
	v_pk_add_f32 v[48:49], v[48:49], v[80:81]
	v_pk_add_f32 v[112:113], v[112:113], v[144:145]
	v_pk_add_f32 v[48:49], v[48:49], v[112:113]
	v_pk_add_f32 v[16:17], v[16:17], v[48:49]
	v_pk_fma_f32 v[222:223], v[16:17], v[16:17], v[222:223]
	v_pk_add_f32 v[50:51], v[50:51], v[82:83]
	v_pk_add_f32 v[114:115], v[114:115], v[146:147]
	v_pk_add_f32 v[50:51], v[50:51], v[114:115]
	v_pk_add_f32 v[18:19], v[18:19], v[50:51]
	v_pk_fma_f32 v[222:223], v[18:19], v[18:19], v[222:223]
	s_waitcnt vmcnt(11)
	v_pk_add_f32 v[52:53], v[52:53], v[84:85]
	v_pk_add_f32 v[116:117], v[116:117], v[148:149]
	v_pk_add_f32 v[52:53], v[52:53], v[116:117]
	v_pk_add_f32 v[20:21], v[20:21], v[52:53]
	v_pk_fma_f32 v[222:223], v[20:21], v[20:21], v[222:223]
	v_pk_add_f32 v[54:55], v[54:55], v[86:87]
	v_pk_add_f32 v[118:119], v[118:119], v[150:151]
	v_pk_add_f32 v[54:55], v[54:55], v[118:119]
	v_pk_add_f32 v[22:23], v[22:23], v[54:55]
	v_pk_fma_f32 v[222:223], v[22:23], v[22:23], v[222:223]
	s_waitcnt vmcnt(10)
	v_pk_add_f32 v[56:57], v[56:57], v[88:89]
	v_pk_add_f32 v[120:121], v[120:121], v[152:153]
	v_pk_add_f32 v[56:57], v[56:57], v[120:121]
	v_pk_add_f32 v[24:25], v[24:25], v[56:57]
	v_pk_fma_f32 v[222:223], v[24:25], v[24:25], v[222:223]
	v_pk_add_f32 v[58:59], v[58:59], v[90:91]
	v_pk_add_f32 v[122:123], v[122:123], v[154:155]
	v_pk_add_f32 v[58:59], v[58:59], v[122:123]
	v_pk_add_f32 v[26:27], v[26:27], v[58:59]
	v_pk_fma_f32 v[222:223], v[26:27], v[26:27], v[222:223]
	s_waitcnt vmcnt(9)
	v_pk_add_f32 v[60:61], v[60:61], v[92:93]
	v_pk_add_f32 v[124:125], v[124:125], v[156:157]
	v_pk_add_f32 v[60:61], v[60:61], v[124:125]
	v_pk_add_f32 v[28:29], v[28:29], v[60:61]
	v_pk_fma_f32 v[222:223], v[28:29], v[28:29], v[222:223]
	v_pk_add_f32 v[62:63], v[62:63], v[94:95]
	v_pk_add_f32 v[126:127], v[126:127], v[158:159]
	v_pk_add_f32 v[62:63], v[62:63], v[126:127]
	v_pk_add_f32 v[30:31], v[30:31], v[62:63]
	v_pk_fma_f32 v[222:223], v[30:31], v[30:31], v[222:223]
	s_waitcnt vmcnt(8)
	v_pk_add_f32 v[64:65], v[64:65], v[96:97]
	v_pk_add_f32 v[128:129], v[128:129], v[160:161]
	v_pk_add_f32 v[64:65], v[64:65], v[128:129]
	v_pk_add_f32 v[32:33], v[32:33], v[64:65]
	v_pk_fma_f32 v[222:223], v[32:33], v[32:33], v[222:223]
	v_pk_add_f32 v[66:67], v[66:67], v[98:99]
	v_pk_add_f32 v[130:131], v[130:131], v[162:163]
	v_pk_add_f32 v[66:67], v[66:67], v[130:131]
	v_pk_add_f32 v[34:35], v[34:35], v[66:67]
	v_pk_fma_f32 v[222:223], v[34:35], v[34:35], v[222:223]
	s_nop 0
	v_add_f32_e32 v224, v222, v223
	ds_bpermute_b32 v225, v208, v224
	s_waitcnt lgkmcnt(0)
	v_add_f32_e32 v224, v224, v225
	ds_bpermute_b32 v225, v209, v224
	s_waitcnt lgkmcnt(0)
	v_add_f32_e32 v224, v224, v225
	ds_bpermute_b32 v225, v164, v224
	s_waitcnt lgkmcnt(0)
	v_add_f32_e32 v224, v224, v225
	ds_bpermute_b32 v225, v165, v224
	s_waitcnt lgkmcnt(0)
	v_add_f32_e32 v224, v224, v225
	ds_bpermute_b32 v225, v166, v224
	s_waitcnt lgkmcnt(0)
	v_add_f32_e32 v224, v224, v225
	ds_bpermute_b32 v225, v167, v224
	s_waitcnt lgkmcnt(0)
	v_add_f32_e32 v224, v224, v225
	v_fmamk_f32 v224, v224, 0x3a000000, v226
	v_rsq_f32_e32 v224, v224
	s_lshl_b32 s13, s12, 13
	s_add_u32 s18, s18, 0x4000000
	s_addc_u32 s19, s19, 0
	s_add_u32 s18, s18, s13
	s_addc_u32 s19, s19, 0
	s_add_u32 s24, s18, 0x1000
	s_addc_u32 s25, s19, 0
	v_readlane_b32 s20, v254, 54
	v_readlane_b32 s21, v254, 55
	s_add_i32 s4, s12, 0x2000
	s_lshl_b32 s13, s4, 12
	s_add_u32 s20, s20, s13
	s_addc_u32 s21, s21, 0
	s_waitcnt vmcnt(0)
	global_store_dwordx4 v0, v[4:7], s[18:19]
	global_store_dwordx4 v0, v[8:11], s[18:19] offset:1024
	global_store_dwordx4 v0, v[12:15], s[18:19] offset:2048
	global_store_dwordx4 v0, v[16:19], s[18:19] offset:3072
	global_store_dwordx4 v0, v[20:23], s[24:25]
	global_store_dwordx4 v0, v[24:27], s[24:25] offset:1024
	global_store_dwordx4 v0, v[28:31], s[24:25] offset:2048
	global_store_dwordx4 v0, v[32:35], s[24:25] offset:3072
	v_pk_mul_f32 v[176:177], v[4:5], v[176:177]
	v_pk_mul_f32 v[178:179], v[6:7], v[178:179]
	v_cvt_pk_bf16_f32 v176, v176, v177
	v_cvt_pk_bf16_f32 v177, v178, v179
	global_store_dwordx2 v1, v[176:177], s[20:21]
	v_pk_mul_f32 v[180:181], v[8:9], v[180:181]
	v_pk_mul_f32 v[182:183], v[10:11], v[182:183]
	v_cvt_pk_bf16_f32 v180, v180, v181
	v_cvt_pk_bf16_f32 v181, v182, v183
	global_store_dwordx2 v1, v[180:181], s[20:21] offset:512
	v_pk_mul_f32 v[184:185], v[12:13], v[184:185]
	v_pk_mul_f32 v[186:187], v[14:15], v[186:187]
	v_cvt_pk_bf16_f32 v184, v184, v185
	v_cvt_pk_bf16_f32 v185, v186, v187
	global_store_dwordx2 v1, v[184:185], s[20:21] offset:1024
	v_pk_mul_f32 v[188:189], v[16:17], v[188:189]
	v_pk_mul_f32 v[190:191], v[18:19], v[190:191]
	v_cvt_pk_bf16_f32 v188, v188, v189
	v_cvt_pk_bf16_f32 v189, v190, v191
	global_store_dwordx2 v1, v[188:189], s[20:21] offset:1536
	v_pk_mul_f32 v[192:193], v[20:21], v[192:193]
	v_pk_mul_f32 v[194:195], v[22:23], v[194:195]
	v_cvt_pk_bf16_f32 v192, v192, v193
	v_cvt_pk_bf16_f32 v193, v194, v195
	global_store_dwordx2 v1, v[192:193], s[20:21] offset:2048
	v_pk_mul_f32 v[196:197], v[24:25], v[196:197]
	v_pk_mul_f32 v[198:199], v[26:27], v[198:199]
	v_cvt_pk_bf16_f32 v196, v196, v197
	v_cvt_pk_bf16_f32 v197, v198, v199
	global_store_dwordx2 v1, v[196:197], s[20:21] offset:2560
	v_pk_mul_f32 v[200:201], v[28:29], v[200:201]
	v_pk_mul_f32 v[202:203], v[30:31], v[202:203]
	v_cvt_pk_bf16_f32 v200, v200, v201
	v_cvt_pk_bf16_f32 v201, v202, v203
	global_store_dwordx2 v1, v[200:201], s[20:21] offset:3072
	v_pk_mul_f32 v[204:205], v[32:33], v[204:205]
	v_pk_mul_f32 v[206:207], v[34:35], v[206:207]
	v_cvt_pk_bf16_f32 v204, v204, v205
	v_cvt_pk_bf16_f32 v205, v206, v207
	global_store_dwordx2 v1, v[204:205], s[20:21] offset:3584
	s_lshl_b32 s4, s4, 2
	s_add_u32 s20, s2, s4
	s_addc_u32 s21, s3, 0
	v_mov_b32_e32 v2, 0
	v_cmp_eq_u32_e32 vcc, 0, v170
	s_and_saveexec_b64 s[24:25], vcc
	global_store_dword v2, v224, s[20:21]
	s_or_b64 exec, exec, s[24:25]


